# nontemporal stores for the sigmoid-gate tiles written by the input projection (consumed two phases later)
# baseline (speedup 1.0000x reference)
; __device__ __forceinline__ float sigmoidf_(float x) { return __builtin_amdgcn_rcpf(1.0f + __builtin_amdgcn_exp2f(-x * LOG2E)); }
; __device__ __forceinline__ u32x4 pack8(const f32x4 v0, const f32x4 v1) { u32x4 w; w.x = cvt_pk_bf16(v0[0], v0[1]); w.y = cvt_pk_bf16(v0[2], v0[3]); w.z = cvt_pk_bf16(v1[0], v1[1]); w.w = cvt_pk_bf16(v1[2], v1[3]); return w; }
;     __device__ __forceinline__ void operator()(const f32x4 (&acc)[2][2][4][2], const Unit& u, int wr, int wc, int fr, int fq) const {
;     ...
;         if (pn >= 13) {
; #pragma unroll
;             for (int ai = 0; ai < 2; ++ai)
; #pragma unroll
;                 for (int m = 0; m < 4; ++m) { bf16_t* rowp = QKG + (size_t)(row0 + ai * HALF + m * 16) * QKG_LD + col0;
; #pragma unroll
;                     for (int bj = 0; bj < 2; ++bj) { f32x4 v0 = acc[ai][bj][m][0], v1 = acc[ai][bj][m][1];
; #pragma unroll
;                         for (int e = 0; e < 4; ++e) { v0[e] = sigmoidf_(v0[e]); v1[e] = sigmoidf_(v1[e]); }
;                         *(u32x4*)(rowp + bj * HALF) = pack8(v0, v1); } }
.LBB0_503:
	s_and_b64 vcc, exec, s[12:13]
	s_cbranch_vccz .LBB0_505
	v_mul_f32_e32 v136, 0xbfb8aa3b, v126
	v_mul_f32_e32 v137, 0xbfb8aa3b, v122
	v_exp_f32_e32 v136, v136
	v_exp_f32_e32 v137, v137
	v_mov_b32_e32 v161, v1
	v_mov_b64_e32 v[132:133], s[84:85]
	v_mad_i64_i32 v[134:135], s[4:5], v199, s88, v[132:133]
	v_lshlrev_b64 v[130:131], 1, v[160:161]
	v_lshl_add_u64 v[138:139], v[134:135], 0, v[130:131]
	v_add_f32_e32 v134, 1.0, v136
	v_add_f32_e32 v135, 1.0, v137
	v_mul_f32_e32 v136, 0xbfb8aa3b, v127
	v_mul_f32_e32 v137, 0xbfb8aa3b, v123
	v_exp_f32_e32 v136, v136
	v_exp_f32_e32 v137, v137
	v_rcp_f32_e32 v140, v135
	v_mul_f32_e32 v141, 0xbfb8aa3b, v124
	v_add_f32_e32 v135, 1.0, v136
	v_add_f32_e32 v136, 1.0, v137
	v_mul_f32_e32 v137, 0xbfb8aa3b, v128
	v_exp_f32_e32 v137, v137
	v_exp_f32_e32 v141, v141
	v_mul_f32_e32 v142, 0xbfb8aa3b, v129
	v_mul_f32_e32 v143, 0xbfb8aa3b, v125
	v_exp_f32_e32 v142, v142
	v_exp_f32_e32 v143, v143
	v_add_f32_e32 v137, 1.0, v137
	v_add_f32_e32 v141, 1.0, v141
	v_rcp_f32_e32 v134, v134
	v_rcp_f32_e32 v135, v135
	v_rcp_f32_e32 v136, v136
	v_rcp_f32_e32 v137, v137
	v_rcp_f32_e32 v141, v141
	v_add_f32_e32 v142, 1.0, v142
	v_add_f32_e32 v143, 1.0, v143
	v_rcp_f32_e32 v142, v142
	v_rcp_f32_e32 v143, v143
	v_cvt_pk_bf16_f32 v134, v134, v135
	v_cvt_pk_bf16_f32 v135, v137, v142
	v_cvt_pk_bf16_f32 v136, v140, v136
	v_cvt_pk_bf16_f32 v137, v141, v143
	v_mul_f32_e32 v141, 0xbfb8aa3b, v106
	v_mul_f32_e32 v140, 0xbfb8aa3b, v114
	v_exp_f32_e32 v141, v141
	global_store_dwordx4 v[138:139], v[134:137], off nt
	v_exp_f32_e32 v140, v140
	v_mul_f32_e32 v142, 0xbfb8aa3b, v117
	v_mul_f32_e32 v136, 0xbfb8aa3b, v115
	v_mul_f32_e32 v137, 0xbfb8aa3b, v107
	v_exp_f32_e32 v136, v136
	v_exp_f32_e32 v137, v137
	v_add_f32_e32 v135, 1.0, v141
	v_add_f32_e32 v134, 1.0, v140
	v_rcp_f32_e32 v140, v135
	v_add_f32_e32 v135, 1.0, v136
	v_add_f32_e32 v136, 1.0, v137
	v_mul_f32_e32 v137, 0xbfb8aa3b, v116
	v_exp_f32_e32 v137, v137
	v_mul_f32_e32 v141, 0xbfb8aa3b, v108
	v_mul_f32_e32 v143, 0xbfb8aa3b, v109
	v_exp_f32_e32 v141, v141
	v_exp_f32_e32 v142, v142
	v_exp_f32_e32 v143, v143
	v_add_f32_e32 v137, 1.0, v137
	v_rcp_f32_e32 v134, v134
	v_rcp_f32_e32 v135, v135
	v_rcp_f32_e32 v136, v136
	v_rcp_f32_e32 v137, v137
	v_add_f32_e32 v141, 1.0, v141
	v_add_f32_e32 v142, 1.0, v142
	v_add_f32_e32 v143, 1.0, v143
	v_rcp_f32_e32 v141, v141
	v_rcp_f32_e32 v142, v142
	v_rcp_f32_e32 v143, v143
	v_cvt_pk_bf16_f32 v134, v134, v135
	v_cvt_pk_bf16_f32 v135, v137, v142
	v_cvt_pk_bf16_f32 v136, v140, v136
	v_cvt_pk_bf16_f32 v137, v141, v143
	global_store_dwordx4 v[138:139], v[134:137], off offset:256 nt
	v_mul_f32_e32 v141, 0xbfb8aa3b, v112
	v_exp_f32_e32 v141, v141
	v_mul_f32_e32 v136, 0xbfb8aa3b, v118
	v_mul_f32_e32 v137, 0xbfb8aa3b, v110
	v_exp_f32_e32 v136, v136
	v_exp_f32_e32 v137, v137
	v_or_b32_e32 v134, 16, v199
	v_mad_i64_i32 v[134:135], s[4:5], v134, s88, v[132:133]
	v_lshl_add_u64 v[138:139], v[134:135], 0, v[130:131]
	v_add_f32_e32 v134, 1.0, v136
	v_add_f32_e32 v135, 1.0, v137
	v_mul_f32_e32 v136, 0xbfb8aa3b, v119
	v_mul_f32_e32 v137, 0xbfb8aa3b, v111
	v_exp_f32_e32 v136, v136
	v_exp_f32_e32 v137, v137
	v_rcp_f32_e32 v140, v135
	v_mul_f32_e32 v142, 0xbfb8aa3b, v121
	v_add_f32_e32 v135, 1.0, v136
	v_add_f32_e32 v136, 1.0, v137
	v_mul_f32_e32 v137, 0xbfb8aa3b, v120
	v_exp_f32_e32 v137, v137
	v_mul_f32_e32 v143, 0xbfb8aa3b, v113
	v_exp_f32_e32 v142, v142
	v_exp_f32_e32 v143, v143
	v_add_f32_e32 v137, 1.0, v137
	v_add_f32_e32 v141, 1.0, v141
	v_rcp_f32_e32 v134, v134
	v_rcp_f32_e32 v135, v135
	v_rcp_f32_e32 v136, v136
	v_rcp_f32_e32 v137, v137
	v_rcp_f32_e32 v141, v141
	v_add_f32_e32 v142, 1.0, v142
	v_add_f32_e32 v143, 1.0, v143
	v_rcp_f32_e32 v142, v142
	v_rcp_f32_e32 v143, v143
	v_cvt_pk_bf16_f32 v134, v134, v135
	v_cvt_pk_bf16_f32 v135, v137, v142
	v_cvt_pk_bf16_f32 v136, v140, v136
	v_cvt_pk_bf16_f32 v137, v141, v143
	v_mul_f32_e32 v141, 0xbfb8aa3b, v90
	v_mul_f32_e32 v140, 0xbfb8aa3b, v98
	v_exp_f32_e32 v141, v141
	global_store_dwordx4 v[138:139], v[134:137], off nt
	v_exp_f32_e32 v140, v140
	v_mul_f32_e32 v142, 0xbfb8aa3b, v101
	v_mul_f32_e32 v136, 0xbfb8aa3b, v99
	v_mul_f32_e32 v137, 0xbfb8aa3b, v91
	v_exp_f32_e32 v136, v136
	v_exp_f32_e32 v137, v137
	v_add_f32_e32 v135, 1.0, v141
	v_add_f32_e32 v134, 1.0, v140
	v_rcp_f32_e32 v140, v135
	v_add_f32_e32 v135, 1.0, v136
	v_add_f32_e32 v136, 1.0, v137
	v_mul_f32_e32 v137, 0xbfb8aa3b, v100
	v_exp_f32_e32 v137, v137
	v_mul_f32_e32 v141, 0xbfb8aa3b, v92
	v_mul_f32_e32 v143, 0xbfb8aa3b, v93
	v_exp_f32_e32 v141, v141
	v_exp_f32_e32 v142, v142
	v_exp_f32_e32 v143, v143
	v_add_f32_e32 v137, 1.0, v137
	v_rcp_f32_e32 v134, v134
	v_rcp_f32_e32 v135, v135
	v_rcp_f32_e32 v136, v136
	v_rcp_f32_e32 v137, v137
	v_add_f32_e32 v141, 1.0, v141
	v_add_f32_e32 v142, 1.0, v142
	v_add_f32_e32 v143, 1.0, v143
	v_rcp_f32_e32 v141, v141
	v_rcp_f32_e32 v142, v142
	v_rcp_f32_e32 v143, v143
	v_cvt_pk_bf16_f32 v134, v134, v135
	v_cvt_pk_bf16_f32 v135, v137, v142
	v_cvt_pk_bf16_f32 v136, v140, v136
	v_cvt_pk_bf16_f32 v137, v141, v143
	global_store_dwordx4 v[138:139], v[134:137], off offset:256 nt
	v_mul_f32_e32 v141, 0xbfb8aa3b, v96
	v_exp_f32_e32 v141, v141
	v_mul_f32_e32 v136, 0xbfb8aa3b, v102
	v_mul_f32_e32 v137, 0xbfb8aa3b, v94
	v_exp_f32_e32 v136, v136
	v_exp_f32_e32 v137, v137
	v_or_b32_e32 v134, 32, v199
	v_mad_i64_i32 v[134:135], s[4:5], v134, s88, v[132:133]
	v_lshl_add_u64 v[138:139], v[134:135], 0, v[130:131]
	v_add_f32_e32 v134, 1.0, v136
	v_add_f32_e32 v135, 1.0, v137
	v_mul_f32_e32 v136, 0xbfb8aa3b, v103
	v_mul_f32_e32 v137, 0xbfb8aa3b, v95
	v_exp_f32_e32 v136, v136
	v_exp_f32_e32 v137, v137
	v_rcp_f32_e32 v140, v135
; __device__ __forceinline__ float sigmoidf_(float x) { return __builtin_amdgcn_rcpf(1.0f + __builtin_amdgcn_exp2f(-x * LOG2E)); }
; __device__ __forceinline__ u32x4 pack8(const f32x4 v0, const f32x4 v1) { u32x4 w; w.x = cvt_pk_bf16(v0[0], v0[1]); w.y = cvt_pk_bf16(v0[2], v0[3]); w.z = cvt_pk_bf16(v1[0], v1[1]); w.w = cvt_pk_bf16(v1[2], v1[3]); return w; }
;     __device__ __forceinline__ void operator()(const f32x4 (&acc)[2][2][4][2], const Unit& u, int wr, int wc, int fr, int fq) const {
;     ...
;             for (int ai = 0; ai < 2; ++ai)
; #pragma unroll
;                 for (int m = 0; m < 4; ++m) { bf16_t* rowp = QKG + (size_t)(row0 + ai * HALF + m * 16) * QKG_LD + col0;
; #pragma unroll
;                     for (int bj = 0; bj < 2; ++bj) { f32x4 v0 = acc[ai][bj][m][0], v1 = acc[ai][bj][m][1];
; #pragma unroll
;                         for (int e = 0; e < 4; ++e) { v0[e] = sigmoidf_(v0[e]); v1[e] = sigmoidf_(v1[e]); }
;                         *(u32x4*)(rowp + bj * HALF) = pack8(v0, v1); } }
	v_mul_f32_e32 v142, 0xbfb8aa3b, v105
	v_add_f32_e32 v135, 1.0, v136
	v_add_f32_e32 v136, 1.0, v137
	v_mul_f32_e32 v137, 0xbfb8aa3b, v104
	v_exp_f32_e32 v137, v137
	v_mul_f32_e32 v143, 0xbfb8aa3b, v97
	v_exp_f32_e32 v142, v142
	v_exp_f32_e32 v143, v143
	v_add_f32_e32 v137, 1.0, v137
	v_add_f32_e32 v141, 1.0, v141
	v_rcp_f32_e32 v134, v134
	v_rcp_f32_e32 v135, v135
	v_rcp_f32_e32 v136, v136
	v_rcp_f32_e32 v137, v137
	v_rcp_f32_e32 v141, v141
	v_add_f32_e32 v142, 1.0, v142
	v_add_f32_e32 v143, 1.0, v143
	v_rcp_f32_e32 v142, v142
	v_rcp_f32_e32 v143, v143
	v_cvt_pk_bf16_f32 v134, v134, v135
	v_cvt_pk_bf16_f32 v135, v137, v142
	v_cvt_pk_bf16_f32 v136, v140, v136
	v_cvt_pk_bf16_f32 v137, v141, v143
	v_mul_f32_e32 v141, 0xbfb8aa3b, v74
	v_mul_f32_e32 v140, 0xbfb8aa3b, v82
	v_exp_f32_e32 v141, v141
	global_store_dwordx4 v[138:139], v[134:137], off nt
	v_exp_f32_e32 v140, v140
	v_mul_f32_e32 v142, 0xbfb8aa3b, v85
	v_mul_f32_e32 v136, 0xbfb8aa3b, v83
	v_mul_f32_e32 v137, 0xbfb8aa3b, v75
	v_exp_f32_e32 v136, v136
	v_exp_f32_e32 v137, v137
	v_add_f32_e32 v135, 1.0, v141
	v_add_f32_e32 v134, 1.0, v140
	v_rcp_f32_e32 v140, v135
	v_add_f32_e32 v135, 1.0, v136
	v_add_f32_e32 v136, 1.0, v137
	v_mul_f32_e32 v137, 0xbfb8aa3b, v84
	v_exp_f32_e32 v137, v137
	v_mul_f32_e32 v141, 0xbfb8aa3b, v76
	v_mul_f32_e32 v143, 0xbfb8aa3b, v77
	v_exp_f32_e32 v141, v141
	v_exp_f32_e32 v142, v142
	v_exp_f32_e32 v143, v143
	v_add_f32_e32 v137, 1.0, v137
	v_rcp_f32_e32 v134, v134
	v_rcp_f32_e32 v135, v135
	v_rcp_f32_e32 v136, v136
	v_rcp_f32_e32 v137, v137
	v_add_f32_e32 v141, 1.0, v141
	v_add_f32_e32 v142, 1.0, v142
	v_add_f32_e32 v143, 1.0, v143
	v_rcp_f32_e32 v141, v141
	v_rcp_f32_e32 v142, v142
	v_rcp_f32_e32 v143, v143
	v_cvt_pk_bf16_f32 v134, v134, v135
	v_cvt_pk_bf16_f32 v135, v137, v142
	v_cvt_pk_bf16_f32 v136, v140, v136
	v_cvt_pk_bf16_f32 v137, v141, v143
	global_store_dwordx4 v[138:139], v[134:137], off offset:256 nt
	v_mul_f32_e32 v141, 0xbfb8aa3b, v80
	v_exp_f32_e32 v141, v141
	v_mul_f32_e32 v136, 0xbfb8aa3b, v86
	v_mul_f32_e32 v137, 0xbfb8aa3b, v78
	v_exp_f32_e32 v136, v136
	v_exp_f32_e32 v137, v137
	v_or_b32_e32 v134, 48, v199
	v_mad_i64_i32 v[134:135], s[4:5], v134, s88, v[132:133]
	v_lshl_add_u64 v[138:139], v[134:135], 0, v[130:131]
	v_add_f32_e32 v134, 1.0, v136
	v_add_f32_e32 v135, 1.0, v137
	v_mul_f32_e32 v136, 0xbfb8aa3b, v87
	v_mul_f32_e32 v137, 0xbfb8aa3b, v79
	v_exp_f32_e32 v136, v136
	v_exp_f32_e32 v137, v137
	v_rcp_f32_e32 v140, v135
	v_mul_f32_e32 v142, 0xbfb8aa3b, v89
	v_add_f32_e32 v135, 1.0, v136
	v_add_f32_e32 v136, 1.0, v137
	v_mul_f32_e32 v137, 0xbfb8aa3b, v88
	v_exp_f32_e32 v137, v137
	v_mul_f32_e32 v143, 0xbfb8aa3b, v81
	v_exp_f32_e32 v142, v142
	v_exp_f32_e32 v143, v143
	v_add_f32_e32 v137, 1.0, v137
	v_add_f32_e32 v141, 1.0, v141
	v_rcp_f32_e32 v134, v134
	v_rcp_f32_e32 v135, v135
	v_rcp_f32_e32 v136, v136
	v_rcp_f32_e32 v137, v137
	v_rcp_f32_e32 v141, v141
	v_add_f32_e32 v142, 1.0, v142
	v_add_f32_e32 v143, 1.0, v143
	v_rcp_f32_e32 v142, v142
	v_rcp_f32_e32 v143, v143
	v_cvt_pk_bf16_f32 v134, v134, v135
	v_cvt_pk_bf16_f32 v135, v137, v142
	v_cvt_pk_bf16_f32 v136, v140, v136
	v_cvt_pk_bf16_f32 v137, v141, v143
	v_mul_f32_e32 v141, 0xbfb8aa3b, v66
	v_mul_f32_e32 v140, 0xbfb8aa3b, v70
	v_exp_f32_e32 v141, v141
	global_store_dwordx4 v[138:139], v[134:137], off nt
	v_exp_f32_e32 v140, v140
	v_mul_f32_e32 v142, 0xbfb8aa3b, v73
	v_mul_f32_e32 v136, 0xbfb8aa3b, v71
	v_mul_f32_e32 v137, 0xbfb8aa3b, v67
	v_exp_f32_e32 v136, v136
	v_exp_f32_e32 v137, v137
	v_add_f32_e32 v135, 1.0, v141
	v_add_f32_e32 v134, 1.0, v140
	v_rcp_f32_e32 v140, v135
	v_add_f32_e32 v135, 1.0, v136
	v_add_f32_e32 v136, 1.0, v137
	v_mul_f32_e32 v137, 0xbfb8aa3b, v72
	v_exp_f32_e32 v137, v137
	v_mul_f32_e32 v141, 0xbfb8aa3b, v68
	v_mul_f32_e32 v143, 0xbfb8aa3b, v69
	v_exp_f32_e32 v141, v141
	v_exp_f32_e32 v142, v142
	v_exp_f32_e32 v143, v143
	v_add_f32_e32 v137, 1.0, v137
	v_rcp_f32_e32 v134, v134
	v_rcp_f32_e32 v135, v135
	v_rcp_f32_e32 v136, v136
	v_rcp_f32_e32 v137, v137
	v_add_f32_e32 v141, 1.0, v141
	v_add_f32_e32 v142, 1.0, v142
	v_add_f32_e32 v143, 1.0, v143
	v_rcp_f32_e32 v141, v141
	v_rcp_f32_e32 v142, v142
	v_rcp_f32_e32 v143, v143
	v_cvt_pk_bf16_f32 v134, v134, v135
	v_cvt_pk_bf16_f32 v135, v137, v142
	v_cvt_pk_bf16_f32 v136, v140, v136
	v_cvt_pk_bf16_f32 v137, v141, v143
	global_store_dwordx4 v[138:139], v[134:137], off offset:256 nt
	v_mul_f32_e32 v141, 0xbfb8aa3b, v60
	v_exp_f32_e32 v141, v141
	v_mul_f32_e32 v136, 0xbfb8aa3b, v62
	v_mul_f32_e32 v137, 0xbfb8aa3b, v58
	v_exp_f32_e32 v136, v136
	v_exp_f32_e32 v137, v137
	v_add_u32_e32 v134, 0x80, v199
	v_mad_i64_i32 v[134:135], s[4:5], v134, s88, v[132:133]
	v_lshl_add_u64 v[138:139], v[134:135], 0, v[130:131]
	v_add_f32_e32 v134, 1.0, v136
	v_add_f32_e32 v135, 1.0, v137
	v_mul_f32_e32 v136, 0xbfb8aa3b, v63
	v_mul_f32_e32 v137, 0xbfb8aa3b, v59
	v_exp_f32_e32 v136, v136
	v_exp_f32_e32 v137, v137
	v_rcp_f32_e32 v140, v135
	v_mul_f32_e32 v142, 0xbfb8aa3b, v65
	v_add_f32_e32 v135, 1.0, v136
	v_add_f32_e32 v136, 1.0, v137
	v_mul_f32_e32 v137, 0xbfb8aa3b, v64
	v_exp_f32_e32 v137, v137
	v_mul_f32_e32 v143, 0xbfb8aa3b, v61
	v_exp_f32_e32 v142, v142
	v_exp_f32_e32 v143, v143
	v_add_f32_e32 v137, 1.0, v137
	v_add_f32_e32 v141, 1.0, v141
	v_rcp_f32_e32 v134, v134
	v_rcp_f32_e32 v135, v135
	v_rcp_f32_e32 v136, v136
	v_rcp_f32_e32 v137, v137
	v_rcp_f32_e32 v141, v141
	v_add_f32_e32 v142, 1.0, v142
	v_add_f32_e32 v143, 1.0, v143
	v_rcp_f32_e32 v142, v142
	v_rcp_f32_e32 v143, v143
	v_cvt_pk_bf16_f32 v134, v134, v135
	v_cvt_pk_bf16_f32 v135, v137, v142
	v_cvt_pk_bf16_f32 v136, v140, v136
	v_cvt_pk_bf16_f32 v137, v141, v143
; __device__ __forceinline__ float sigmoidf_(float x) { return __builtin_amdgcn_rcpf(1.0f + __builtin_amdgcn_exp2f(-x * LOG2E)); }
; __device__ __forceinline__ u32x4 pack8(const f32x4 v0, const f32x4 v1) { u32x4 w; w.x = cvt_pk_bf16(v0[0], v0[1]); w.y = cvt_pk_bf16(v0[2], v0[3]); w.z = cvt_pk_bf16(v1[0], v1[1]); w.w = cvt_pk_bf16(v1[2], v1[3]); return w; }
;     __device__ __forceinline__ void operator()(const f32x4 (&acc)[2][2][4][2], const Unit& u, int wr, int wc, int fr, int fq) const {
;     ...
;             for (int ai = 0; ai < 2; ++ai)
; #pragma unroll
;                 for (int m = 0; m < 4; ++m) { bf16_t* rowp = QKG + (size_t)(row0 + ai * HALF + m * 16) * QKG_LD + col0;
; #pragma unroll
;                     for (int bj = 0; bj < 2; ++bj) { f32x4 v0 = acc[ai][bj][m][0], v1 = acc[ai][bj][m][1];
; #pragma unroll
;                         for (int e = 0; e < 4; ++e) { v0[e] = sigmoidf_(v0[e]); v1[e] = sigmoidf_(v1[e]); }
;                         *(u32x4*)(rowp + bj * HALF) = pack8(v0, v1); } }
	v_mul_f32_e32 v141, 0xbfb8aa3b, v42
	v_mul_f32_e32 v140, 0xbfb8aa3b, v50
	v_exp_f32_e32 v141, v141
	global_store_dwordx4 v[138:139], v[134:137], off nt
	v_exp_f32_e32 v140, v140
	v_mul_f32_e32 v142, 0xbfb8aa3b, v53
	v_mul_f32_e32 v136, 0xbfb8aa3b, v51
	v_mul_f32_e32 v137, 0xbfb8aa3b, v43
	v_exp_f32_e32 v136, v136
	v_exp_f32_e32 v137, v137
	v_add_f32_e32 v135, 1.0, v141
	v_add_f32_e32 v134, 1.0, v140
	v_rcp_f32_e32 v140, v135
	v_add_f32_e32 v135, 1.0, v136
	v_add_f32_e32 v136, 1.0, v137
	v_mul_f32_e32 v137, 0xbfb8aa3b, v52
	v_exp_f32_e32 v137, v137
	v_mul_f32_e32 v141, 0xbfb8aa3b, v44
	v_mul_f32_e32 v143, 0xbfb8aa3b, v45
	v_exp_f32_e32 v141, v141
	v_exp_f32_e32 v142, v142
	v_exp_f32_e32 v143, v143
	v_add_f32_e32 v137, 1.0, v137
	v_rcp_f32_e32 v134, v134
	v_rcp_f32_e32 v135, v135
	v_rcp_f32_e32 v136, v136
	v_rcp_f32_e32 v137, v137
	v_add_f32_e32 v141, 1.0, v141
	v_add_f32_e32 v142, 1.0, v142
	v_add_f32_e32 v143, 1.0, v143
	v_rcp_f32_e32 v141, v141
	v_rcp_f32_e32 v142, v142
	v_rcp_f32_e32 v143, v143
	v_cvt_pk_bf16_f32 v134, v134, v135
	v_cvt_pk_bf16_f32 v135, v137, v142
	v_cvt_pk_bf16_f32 v136, v140, v136
	v_cvt_pk_bf16_f32 v137, v141, v143
	global_store_dwordx4 v[138:139], v[134:137], off offset:256 nt
	v_mul_f32_e32 v141, 0xbfb8aa3b, v48
	v_exp_f32_e32 v141, v141
	v_mul_f32_e32 v136, 0xbfb8aa3b, v54
	v_mul_f32_e32 v137, 0xbfb8aa3b, v46
	v_exp_f32_e32 v136, v136
	v_exp_f32_e32 v137, v137
	v_add_u32_e32 v134, 0x90, v199
	v_mad_i64_i32 v[134:135], s[4:5], v134, s88, v[132:133]
	v_lshl_add_u64 v[138:139], v[134:135], 0, v[130:131]
	v_add_f32_e32 v134, 1.0, v136
	v_add_f32_e32 v135, 1.0, v137
	v_mul_f32_e32 v136, 0xbfb8aa3b, v55
	v_mul_f32_e32 v137, 0xbfb8aa3b, v47
	v_exp_f32_e32 v136, v136
	v_exp_f32_e32 v137, v137
	v_rcp_f32_e32 v140, v135
	v_mul_f32_e32 v142, 0xbfb8aa3b, v57
	v_add_f32_e32 v135, 1.0, v136
	v_add_f32_e32 v136, 1.0, v137
	v_mul_f32_e32 v137, 0xbfb8aa3b, v56
	v_exp_f32_e32 v137, v137
	v_mul_f32_e32 v143, 0xbfb8aa3b, v49
	v_exp_f32_e32 v142, v142
	v_exp_f32_e32 v143, v143
	v_add_f32_e32 v137, 1.0, v137
	v_add_f32_e32 v141, 1.0, v141
	v_rcp_f32_e32 v134, v134
	v_rcp_f32_e32 v135, v135
	v_rcp_f32_e32 v136, v136
	v_rcp_f32_e32 v137, v137
	v_rcp_f32_e32 v141, v141
	v_add_f32_e32 v142, 1.0, v142
	v_add_f32_e32 v143, 1.0, v143
	v_rcp_f32_e32 v142, v142
	v_rcp_f32_e32 v143, v143
	v_cvt_pk_bf16_f32 v134, v134, v135
	v_cvt_pk_bf16_f32 v135, v137, v142
	v_cvt_pk_bf16_f32 v136, v140, v136
	v_cvt_pk_bf16_f32 v137, v141, v143
	v_mul_f32_e32 v141, 0xbfb8aa3b, v26
	v_mul_f32_e32 v140, 0xbfb8aa3b, v34
	v_exp_f32_e32 v141, v141
	global_store_dwordx4 v[138:139], v[134:137], off nt
	v_exp_f32_e32 v140, v140
	v_mul_f32_e32 v142, 0xbfb8aa3b, v37
	v_mul_f32_e32 v136, 0xbfb8aa3b, v35
	v_mul_f32_e32 v137, 0xbfb8aa3b, v27
	v_exp_f32_e32 v136, v136
	v_exp_f32_e32 v137, v137
	v_add_f32_e32 v135, 1.0, v141
	v_add_f32_e32 v134, 1.0, v140
	v_rcp_f32_e32 v140, v135
	v_add_f32_e32 v135, 1.0, v136
	v_add_f32_e32 v136, 1.0, v137
	v_mul_f32_e32 v137, 0xbfb8aa3b, v36
	v_exp_f32_e32 v137, v137
	v_mul_f32_e32 v141, 0xbfb8aa3b, v28
	v_mul_f32_e32 v143, 0xbfb8aa3b, v29
	v_exp_f32_e32 v141, v141
	v_exp_f32_e32 v142, v142
	v_exp_f32_e32 v143, v143
	v_add_f32_e32 v137, 1.0, v137
	v_rcp_f32_e32 v134, v134
	v_rcp_f32_e32 v135, v135
	v_rcp_f32_e32 v136, v136
	v_rcp_f32_e32 v137, v137
	v_add_f32_e32 v141, 1.0, v141
	v_add_f32_e32 v142, 1.0, v142
	v_add_f32_e32 v143, 1.0, v143
	v_rcp_f32_e32 v141, v141
	v_rcp_f32_e32 v142, v142
	v_rcp_f32_e32 v143, v143
	v_cvt_pk_bf16_f32 v134, v134, v135
	v_cvt_pk_bf16_f32 v135, v137, v142
	v_cvt_pk_bf16_f32 v136, v140, v136
	v_cvt_pk_bf16_f32 v137, v141, v143
	global_store_dwordx4 v[138:139], v[134:137], off offset:256 nt
	v_mul_f32_e32 v141, 0xbfb8aa3b, v32
	v_exp_f32_e32 v141, v141
	v_mul_f32_e32 v136, 0xbfb8aa3b, v38
	v_mul_f32_e32 v137, 0xbfb8aa3b, v30
	v_exp_f32_e32 v136, v136
	v_exp_f32_e32 v137, v137
	v_add_u32_e32 v134, 0xa0, v199
	v_mad_i64_i32 v[134:135], s[4:5], v134, s88, v[132:133]
	v_lshl_add_u64 v[138:139], v[134:135], 0, v[130:131]
	v_add_f32_e32 v134, 1.0, v136
	v_add_f32_e32 v135, 1.0, v137
	v_mul_f32_e32 v136, 0xbfb8aa3b, v39
	v_mul_f32_e32 v137, 0xbfb8aa3b, v31
	v_exp_f32_e32 v136, v136
	v_exp_f32_e32 v137, v137
	v_rcp_f32_e32 v140, v135
	v_mul_f32_e32 v142, 0xbfb8aa3b, v41
	v_add_f32_e32 v135, 1.0, v136
; __device__ __forceinline__ float sigmoidf_(float x) { return __builtin_amdgcn_rcpf(1.0f + __builtin_amdgcn_exp2f(-x * LOG2E)); }
; __device__ __forceinline__ u32x4 pack8(const f32x4 v0, const f32x4 v1) { u32x4 w; w.x = cvt_pk_bf16(v0[0], v0[1]); w.y = cvt_pk_bf16(v0[2], v0[3]); w.z = cvt_pk_bf16(v1[0], v1[1]); w.w = cvt_pk_bf16(v1[2], v1[3]); return w; }
;     __device__ __forceinline__ void operator()(const f32x4 (&acc)[2][2][4][2], const Unit& u, int wr, int wc, int fr, int fq) const {
;     ...
;             for (int ai = 0; ai < 2; ++ai)
; #pragma unroll
;                 for (int m = 0; m < 4; ++m) { bf16_t* rowp = QKG + (size_t)(row0 + ai * HALF + m * 16) * QKG_LD + col0;
; #pragma unroll
;                     for (int bj = 0; bj < 2; ++bj) { f32x4 v0 = acc[ai][bj][m][0], v1 = acc[ai][bj][m][1];
; #pragma unroll
;                         for (int e = 0; e < 4; ++e) { v0[e] = sigmoidf_(v0[e]); v1[e] = sigmoidf_(v1[e]); }
;                         *(u32x4*)(rowp + bj * HALF) = pack8(v0, v1); } }
	v_add_f32_e32 v136, 1.0, v137
	v_mul_f32_e32 v137, 0xbfb8aa3b, v40
	v_exp_f32_e32 v137, v137
	v_mul_f32_e32 v143, 0xbfb8aa3b, v33
	v_exp_f32_e32 v142, v142
	v_exp_f32_e32 v143, v143
	v_add_f32_e32 v137, 1.0, v137
	v_add_f32_e32 v141, 1.0, v141
	v_rcp_f32_e32 v134, v134
	v_rcp_f32_e32 v135, v135
	v_rcp_f32_e32 v136, v136
	v_rcp_f32_e32 v137, v137
	v_rcp_f32_e32 v141, v141
	v_add_f32_e32 v142, 1.0, v142
	v_add_f32_e32 v143, 1.0, v143
	v_rcp_f32_e32 v142, v142
	v_rcp_f32_e32 v143, v143
	v_cvt_pk_bf16_f32 v134, v134, v135
	v_cvt_pk_bf16_f32 v135, v137, v142
	v_cvt_pk_bf16_f32 v136, v140, v136
	v_cvt_pk_bf16_f32 v137, v141, v143
	v_mul_f32_e32 v141, 0xbfb8aa3b, v10
	v_mul_f32_e32 v140, 0xbfb8aa3b, v18
	v_exp_f32_e32 v141, v141
	global_store_dwordx4 v[138:139], v[134:137], off nt
	v_exp_f32_e32 v140, v140
	v_mul_f32_e32 v142, 0xbfb8aa3b, v21
	v_mul_f32_e32 v136, 0xbfb8aa3b, v19
	v_mul_f32_e32 v137, 0xbfb8aa3b, v11
	v_exp_f32_e32 v136, v136
	v_exp_f32_e32 v137, v137
	v_add_f32_e32 v135, 1.0, v141
	v_add_f32_e32 v134, 1.0, v140
	v_rcp_f32_e32 v140, v135
	v_add_f32_e32 v135, 1.0, v136
	v_add_f32_e32 v136, 1.0, v137
	v_mul_f32_e32 v137, 0xbfb8aa3b, v20
	v_exp_f32_e32 v137, v137
	v_mul_f32_e32 v141, 0xbfb8aa3b, v12
	v_mul_f32_e32 v143, 0xbfb8aa3b, v13
	v_exp_f32_e32 v141, v141
	v_exp_f32_e32 v142, v142
	v_exp_f32_e32 v143, v143
	v_rcp_f32_e32 v134, v134
	v_add_f32_e32 v137, 1.0, v137
	v_rcp_f32_e32 v135, v135
	v_rcp_f32_e32 v136, v136
	v_rcp_f32_e32 v137, v137
	v_add_f32_e32 v141, 1.0, v141
	v_add_f32_e32 v142, 1.0, v142
	v_add_f32_e32 v143, 1.0, v143
	v_cvt_pk_bf16_f32 v134, v134, v135
	v_rcp_f32_e32 v141, v141
	v_rcp_f32_e32 v142, v142
	v_rcp_f32_e32 v143, v143
	v_cvt_pk_bf16_f32 v135, v137, v142
	v_cvt_pk_bf16_f32 v136, v140, v136
	v_cvt_pk_bf16_f32 v137, v141, v143
	global_store_dwordx4 v[138:139], v[134:137], off offset:256 nt
	v_mul_f32_e32 v138, 0xbfb8aa3b, v25
	v_mul_f32_e32 v139, 0xbfb8aa3b, v17
	v_add_u32_e32 v134, 0xb0, v199
	v_mad_i64_i32 v[132:133], s[4:5], v134, s88, v[132:133]
	v_mul_f32_e32 v134, 0xbfb8aa3b, v22
	v_exp_f32_e32 v136, v134
	v_mul_f32_e32 v134, 0xbfb8aa3b, v14
	v_exp_f32_e32 v137, v134
	v_lshl_add_u64 v[134:135], v[132:133], 0, v[130:131]
	v_mul_f32_e32 v132, 0xbfb8aa3b, v23
	v_mul_f32_e32 v133, 0xbfb8aa3b, v15
	v_exp_f32_e32 v132, v132
	v_exp_f32_e32 v133, v133
	v_add_f32_e32 v131, 1.0, v137
	v_add_f32_e32 v130, 1.0, v136
	v_rcp_f32_e32 v136, v131
	v_add_f32_e32 v131, 1.0, v132
	v_add_f32_e32 v132, 1.0, v133
	v_mul_f32_e32 v133, 0xbfb8aa3b, v24
	v_mul_f32_e32 v137, 0xbfb8aa3b, v16
	v_exp_f32_e32 v133, v133
	v_exp_f32_e32 v137, v137
	v_exp_f32_e32 v138, v138
	v_exp_f32_e32 v139, v139
	v_add_f32_e32 v133, 1.0, v133
	v_add_f32_e32 v137, 1.0, v137
	v_rcp_f32_e32 v130, v130
	v_rcp_f32_e32 v131, v131
	v_rcp_f32_e32 v132, v132
	v_rcp_f32_e32 v133, v133
	v_rcp_f32_e32 v137, v137
	v_add_f32_e32 v138, 1.0, v138
	v_add_f32_e32 v139, 1.0, v139
	v_rcp_f32_e32 v138, v138
	v_rcp_f32_e32 v139, v139
	v_cvt_pk_bf16_f32 v130, v130, v131
	v_cvt_pk_bf16_f32 v131, v133, v138
	v_cvt_pk_bf16_f32 v132, v136, v132
	v_cvt_pk_bf16_f32 v133, v137, v139
	v_mul_f32_e32 v137, 0xbfb8aa3b, v2
	v_mul_f32_e32 v136, 0xbfb8aa3b, v6
	v_exp_f32_e32 v137, v137
	global_store_dwordx4 v[134:135], v[130:133], off nt
	v_exp_f32_e32 v136, v136
	v_mul_f32_e32 v138, 0xbfb8aa3b, v9
	v_mul_f32_e32 v132, 0xbfb8aa3b, v7
	v_mul_f32_e32 v133, 0xbfb8aa3b, v3
	v_exp_f32_e32 v132, v132
	v_exp_f32_e32 v133, v133
	v_add_f32_e32 v131, 1.0, v137
	v_add_f32_e32 v130, 1.0, v136
	v_rcp_f32_e32 v136, v131
	v_add_f32_e32 v131, 1.0, v132
	v_add_f32_e32 v132, 1.0, v133
	v_mul_f32_e32 v133, 0xbfb8aa3b, v8
	v_exp_f32_e32 v133, v133
	v_mul_f32_e32 v137, 0xbfb8aa3b, v4
	v_mul_f32_e32 v139, 0xbfb8aa3b, v5
	v_exp_f32_e32 v137, v137
	v_exp_f32_e32 v138, v138
	v_exp_f32_e32 v139, v139
	v_add_f32_e32 v133, 1.0, v133
	v_rcp_f32_e32 v130, v130
	v_rcp_f32_e32 v131, v131
	v_rcp_f32_e32 v132, v132
	v_rcp_f32_e32 v133, v133
	v_add_f32_e32 v137, 1.0, v137
	v_add_f32_e32 v138, 1.0, v138
	v_add_f32_e32 v139, 1.0, v139
	v_rcp_f32_e32 v137, v137
	v_rcp_f32_e32 v138, v138
	v_rcp_f32_e32 v139, v139
	v_cvt_pk_bf16_f32 v130, v130, v131
	v_cvt_pk_bf16_f32 v131, v133, v138
	v_cvt_pk_bf16_f32 v132, v136, v132
	v_cvt_pk_bf16_f32 v133, v137, v139
	global_store_dwordx4 v[134:135], v[130:133], off offset:256 nt
